# prologue de-serialisation: GEMM phase prologues issue the first eight stage LDS-DMA loads right behind the row-statistics loads; the reduction runs afterwards with counted waits
# baseline (speedup 1.0000x reference)
; #define LAS __attribute__((address_space(3)))
; __device__ __forceinline__ int tidx() { int t = threadIdx.x; asm volatile("" : "+v"(t)); return t; }
; __device__ __forceinline__ int prow0(int pm) { return (pm >> 4) * LP + PADR + (pm & 15) * 256; }
; __device__ __forceinline__ int trow(int i) { return (i >> 4) * LP + 4144 + (i & 15); }
;     __device__ __forceinline__ void prep(int pm, int par, LAS unsigned char* lds) const { if (fold) prep_rowstats(stat, pm, par, lds); }
;     __device__ __forceinline__ void prep(int pm, int par, LAS unsigned char* lds) const { if (!ident) prep_rowstats(stat, pm, par, lds); }
;     __device__ __forceinline__ void prep(int pm, int par, LAS unsigned char* lds) const { prep_rowstats(stat, pm, par, lds); }
; #define G_STAGE(bufoff, gbase) do { _Pragma("unroll") for (int _i = 0; _i < 2; ++_i) \
;         __builtin_amdgcn_global_load_lds((const unsigned*)((const char*)(gbase) + voff[_i]), (LAS unsigned*)(lds + (bufoff) + ldsw + _i * 8192), 16, 0, 0); } while (0)
; __device__ __forceinline__ void prep_rowstats(const float* stat, int pm, int par, LAS unsigned char* lds) {
;     const int t = tidx();
;     if (t < (pm < 64 ? 256 : 64)) {
;         const int row = pm < 64 ? prow0(pm) + t : trow(t); const f32x4* sp = (const f32x4*)(stat + (size_t)row * 32);
;         float s1 = 0.f, s2 = 0.f;
; #pragma unroll
;         for (int q = 0; q < 8; ++q) { const f32x4 v = sp[q]; s1 += v[0] + v[2]; s2 += v[1] + v[3]; }
;         const float mu = s1 * (1.0f / 1024.0f); const float var = fmaxf(s2 * (1.0f / 1024.0f) - mu * mu, 0.f);
;         ((LAS f32x2*)(lds + RS_OFF + par * 2048))[t] = (f32x2){mu, __builtin_amdgcn_rsqf(var + LN_EPS)};
;     }
; }
; template <class Epi>
; __device__ __forceinline__ void gemm_phase(LAS unsigned char* lds, const bf16_t* Ag, const bf16_t* Btg, const int K, const int nM, const int nN, const Epi& E) {
;     ...
;     const char* cA = (const char*)Ag + (size_t)prow0(pm) * rstep; const char* cB = (const char*)Btg + (size_t)pn * tstep;
;     E.prep(pm, par, lds);
;     G_STAGE(G_SB(0, 0), cB); G_STAGE(G_SA(0, 0), cA); G_STAGE(G_SB(0, 1), cB + hstep); G_STAGE(G_SA(0, 1), cA + hstep);
.LBB0_65:
	v_readlane_b32 s14, v253, 7
	s_waitcnt vmcnt(16)
	v_mov_b32_e32 v16, v198
	v_readlane_b32 s15, v253, 8
	s_load_dword s12, s[14:15], 0x10
	s_load_dword s20, s[14:15], 0x0
	s_add_u32 s24, s84, 0x2900000
	s_addc_u32 s25, s85, 0
	v_readlane_b32 s14, v253, 25
	s_waitcnt lgkmcnt(0)
	s_lshr_b32 s12, s12, 16
	s_cmp_lg_u32 s12, 0
	s_cselect_b64 s[12:13], -1, 0
	v_cndmask_b32_e64 v0, 0, 1, s[12:13]
	s_cmp_lg_u64 s[12:13], 0
	v_readlane_b32 s15, v253, 26
	v_readfirstlane_b32 s56, v16
	s_addc_u32 s13, s20, 0
	s_andn2_b64 vcc, exec, s[14:15]
	v_readfirstlane_b32 s21, v0
	s_mov_b32 s79, 0
	s_cbranch_vccnz .LBB0_87
	v_mov_b32_e32 v112, v198
	s_nop 0
	v_cmp_gt_i32_e32 vcc, s1, v112
	s_and_saveexec_b64 s[40:41], vcc
	s_cbranch_execz .LBB0_68
	s_mov_b32 s79, 1
	v_readlane_b32 s14, v253, 47
	v_readlane_b32 s15, v253, 48
	s_nop 0
	v_add_u32_e32 v114, s14, v112
	v_ashrrev_i32_e32 v115, 31, v114
	v_lshlrev_b64 v[114:115], 7, v[114:115]
	v_lshl_add_u64 v[114:115], s[18:19], 0, v[114:115]
	global_load_dwordx4 v[72:75], v[114:115], off
	global_load_dwordx4 v[76:79], v[114:115], off offset:16
	global_load_dwordx4 v[82:85], v[114:115], off offset:32
	global_load_dwordx4 v[86:89], v[114:115], off offset:48
	global_load_dwordx4 v[90:93], v[114:115], off offset:64
	global_load_dwordx4 v[94:97], v[114:115], off offset:80
	global_load_dwordx4 v[98:101], v[114:115], off offset:96
	global_load_dwordx4 v[102:105], v[114:115], off offset:112
.LBB0_68:
	s_or_b64 exec, exec, s[40:41]
	v_ashrrev_i32_e32 v0, 31, v16
	v_lshrrev_b32_e32 v0, 26, v0
	v_add_u32_e32 v0, v16, v0
	v_ashrrev_i32_e32 v17, 6, v0
	v_bfe_i32 v0, v16, 27, 1
	v_lshlrev_b32_e32 v2, 4, v16
	v_lshrrev_b32_e32 v0, 22, v0
	v_add_u32_e32 v0, v2, v0
	v_and_b32_e32 v0, 0xfffffc00, v0
	v_sub_u32_e32 v0, v2, v0
	v_lshrrev_b32_e32 v3, 4, v0
	v_bitop3_b32 v3, v3, v0, 32 bitop3:0x6c
	v_ashrrev_i32_e32 v0, 31, v0
	v_lshrrev_b32_e32 v0, 26, v0
	v_add_u32_e32 v0, v3, v0
	v_ashrrev_i32_e32 v18, 6, v0
	v_mul_i32_i24_e32 v9, 64, v18
	v_sub_u32_e32 v3, v3, v9
	v_lshlrev_b32_e32 v8, 3, v17
	v_lshlrev_b32_e32 v0, 5, v17
	v_ashrrev_i16_sdwa v3, v203, sext(v3) dst_sel:DWORD dst_unused:UNUSED_PAD src0_sel:DWORD src1_sel:BYTE_0
	v_and_b32_e32 v8, 0x1ffff0, v8
	v_and_b32_e32 v0, 32, v0
	v_bfe_i32 v19, v3, 0, 16
	v_add_u32_e32 v0, v0, v19
	v_add_lshl_u32 v3, v18, v8, 11
	v_add_u32_e32 v2, 0x2000, v2
	v_lshl_add_u32 v0, v0, 1, v3
	v_ashrrev_i32_e32 v3, 31, v2
	v_lshrrev_b32_e32 v3, 22, v3
	v_add_u32_e32 v3, v2, v3
	s_waitcnt vmcnt(13)
	v_ashrrev_i32_e32 v20, 10, v3
	v_mul_i32_i24_e32 v3, 0x400, v20
	v_sub_u32_e32 v2, v2, v3
	v_lshrrev_b32_e32 v3, 4, v2
	v_bitop3_b32 v2, v3, v2, 32 bitop3:0x6c
	v_ashrrev_i32_e32 v8, 31, v2
	s_ashr_i32 s14, s56, 6
	v_lshrrev_b32_e32 v8, 26, v8
	s_ashr_i32 s12, s56, 8
	v_add_u32_e32 v8, v2, v8
	s_lshl_b32 s57, s14, 10
	v_readlane_b32 s40, v253, 28
	v_ashrrev_i32_e32 v21, 6, v8
	v_and_b32_e32 v8, 0xc0, v8
	v_readlane_b32 s41, v253, 29
	s_add_u32 s50, s36, s40
	v_sub_u32_e32 v2, v2, v8
	s_addc_u32 s51, s37, s41
	v_readlane_b32 s40, v253, 30
	v_lshlrev_b32_e32 v3, 3, v20
	v_lshlrev_b32_e32 v9, 5, v20
	v_ashrrev_i16_sdwa v2, v203, sext(v2) dst_sel:DWORD dst_unused:UNUSED_PAD src0_sel:DWORD src1_sel:BYTE_0
	v_readlane_b32 s41, v253, 31
	s_add_u32 s52, s24, s40
	v_and_b32_e32 v3, 0x1ffff0, v3
	v_and_b32_e32 v9, 32, v9
	v_bfe_i32 v22, v2, 0, 16
	s_addc_u32 s53, s25, s41
	s_add_i32 s58, s57, 0
	v_add_u32_e32 v2, v9, v22
	v_add_lshl_u32 v3, v21, v3, 11
	s_add_i32 m0, s58, 0x10000
	v_lshl_add_u32 v2, v2, 1, v3
	global_load_lds_dwordx4 v0, s[52:53]
	s_add_i32 m0, s58, 0x12000
	s_add_i32 s59, s58, 0x2000
	global_load_lds_dwordx4 v2, s[52:53]
	s_mov_b32 m0, s58
	s_add_u32 s40, s52, 0x40000
	global_load_lds_dwordx4 v0, s[50:51]
	s_mov_b32 m0, s59
	s_addc_u32 s41, s53, 0
	global_load_lds_dwordx4 v2, s[50:51]
	s_add_i32 m0, s58, 0x14000
	v_mov_b32_e32 v3, v1
	global_load_lds_dwordx4 v0, s[40:41]
	s_add_i32 m0, s58, 0x16000
	v_lshl_add_u64 v[14:15], s[52:53], 0, v[0:1]
	global_load_lds_dwordx4 v2, s[40:41]
	s_add_u32 s40, s50, 0x40000
	s_addc_u32 s41, s51, 0
	s_add_i32 s60, s58, 0x4000
	s_mov_b32 m0, s60
	s_add_i32 s61, s58, 0x6000
	global_load_lds_dwordx4 v0, s[40:41]
	s_mov_b32 m0, s61
	v_lshl_add_u64 v[12:13], s[52:53], 0, v[2:3]
	global_load_lds_dwordx4 v2, s[40:41]
	v_lshl_add_u64 v[10:11], s[50:51], 0, v[0:1]
	s_cmp_eq_u32 s79, 0
	s_cbranch_scc1 .Lprol72_b
	v_cmp_gt_i32_e32 vcc, s1, v198
	s_and_saveexec_b64 s[70:71], vcc
	s_cbranch_execz .Lprol72_x
	v_lshl_add_u32 v112, v112, 3, 0
	v_add_u32_e32 v112, 0x20000, v112
	s_waitcnt vmcnt(15)
	v_pk_add_f32 v[114:115], v[72:73], v[74:75]
	s_waitcnt vmcnt(14)
	v_pk_add_f32 v[72:73], v[76:77], v[78:79]
	v_pk_add_f32 v[114:115], v[114:115], 0 op_sel_hi:[1,0]
	s_waitcnt vmcnt(13)
	v_pk_add_f32 v[74:75], v[82:83], v[84:85]
	v_pk_add_f32 v[114:115], v[114:115], v[72:73]
	s_waitcnt vmcnt(12)
	v_pk_add_f32 v[76:77], v[86:87], v[88:89]
	v_pk_add_f32 v[114:115], v[114:115], v[74:75]
	s_waitcnt vmcnt(11)
	v_pk_add_f32 v[78:79], v[90:91], v[92:93]
	v_pk_add_f32 v[114:115], v[114:115], v[76:77]
	s_waitcnt vmcnt(10)
	v_pk_add_f32 v[82:83], v[94:95], v[96:97]
	v_pk_add_f32 v[114:115], v[114:115], v[78:79]
	s_waitcnt vmcnt(9)
	v_pk_add_f32 v[84:85], v[98:99], v[100:101]
	v_pk_add_f32 v[114:115], v[114:115], v[82:83]
	s_waitcnt vmcnt(8)
	v_pk_add_f32 v[72:73], v[102:103], v[104:105]
	v_pk_add_f32 v[114:115], v[114:115], v[84:85]
	s_nop 0
	v_pk_add_f32 v[114:115], v[114:115], v[72:73]
	s_nop 0
	v_pk_mul_f32 v[114:115], v[114:115], s[0:1] op_sel_hi:[1,0]
	s_nop 0
	v_fma_f32 v115, -v114, v114, v115
	v_max_f32_e32 v115, 0, v115
	v_add_f32_e32 v115, 0x3727c5ac, v115
	v_rsq_f32_e32 v115, v115
	ds_write_b64 v112, v[114:115]

; #define G_STAGE(bufoff, gbase) do { _Pragma("unroll") for (int _i = 0; _i < 2; ++_i) \
;         __builtin_amdgcn_global_load_lds((const unsigned*)((const char*)(gbase) + voff[_i]), (LAS unsigned*)(lds + (bufoff) + ldsw + _i * 8192), 16, 0, 0); } while (0)
; #define G_WAIT_V(n) asm volatile("s_waitcnt vmcnt(" #n ")" ::: "memory")
; #define G_BAR __builtin_amdgcn_s_barrier()
; template <class Epi>
; __device__ __forceinline__ void gemm_phase(LAS unsigned char* lds, const bf16_t* Ag, const bf16_t* Btg, const int K, const int nM, const int nN, const Epi& E) {
;     ...
;     G_STAGE(G_SB(0, 0), cB); G_STAGE(G_SA(0, 0), cA); G_STAGE(G_SB(0, 1), cB + hstep); G_STAGE(G_SA(0, 1), cA + hstep);
;     if (wr == 1) G_BAR;
;     G_WAIT_V(4); G_BAR;
.Lprol72_b:
	s_cmp_lg_u32 s12, 1
	v_lshl_add_u64 v[8:9], s[50:51], 0, v[2:3]
	s_cbranch_scc1 .LBB0_70
	s_barrier

; #define LAS __attribute__((address_space(3)))
; __device__ __forceinline__ int tidx() { int t = threadIdx.x; asm volatile("" : "+v"(t)); return t; }
; __device__ __forceinline__ int prow0(int pm) { return (pm >> 4) * LP + PADR + (pm & 15) * 256; }
; __device__ __forceinline__ int trow(int i) { return (i >> 4) * LP + 4144 + (i & 15); }
; __device__ __forceinline__ void prep_rowstats(const float* stat, int pm, int par, LAS unsigned char* lds) {
;     const int t = tidx();
;     if (t < (pm < 64 ? 256 : 64)) {
;         const int row = pm < 64 ? prow0(pm) + t : trow(t); const f32x4* sp = (const f32x4*)(stat + (size_t)row * 32);
;         float s1 = 0.f, s2 = 0.f;
; #pragma unroll
;         for (int q = 0; q < 8; ++q) { const f32x4 v = sp[q]; s1 += v[0] + v[2]; s2 += v[1] + v[3]; }
.LBB0_137:
	v_readlane_b32 s12, v253, 7
	s_waitcnt vmcnt(17) lgkmcnt(1)
	v_mov_b32_e32 v8, v198
	v_readlane_b32 s13, v253, 8
	s_load_dword s13, s[12:13], 0x0
	s_add_u32 s50, s86, 0x6180000
	v_readlane_b32 s14, v253, 20
	s_addc_u32 s51, s87, 0
	v_readlane_b32 s15, v253, 21
	s_add_u32 s46, s84, 0x2700000
	s_addc_u32 s47, s85, 0
	v_cndmask_b32_e64 v0, 0, 1, s[14:15]
	v_cmp_ne_u32_e64 s[42:43], 1, v0
	s_andn2_b64 vcc, exec, s[14:15]
	v_readfirstlane_b32 s20, v8
	s_cbranch_vccnz .LBB0_266
	s_and_b64 vcc, exec, s[40:41]
	s_mov_b32 s69, 0
	s_cbranch_vccnz .LBB0_142
	v_mov_b32_e32 v112, v198
	s_nop 0
	v_cmp_gt_i32_e32 vcc, s1, v112
	s_and_saveexec_b64 s[44:45], vcc
	s_cbranch_execz .LBB0_141
	s_mov_b32 s69, 1
	v_readlane_b32 s14, v253, 47
	v_readlane_b32 s15, v253, 48
	s_nop 0
	v_add_u32_e32 v114, s14, v112
	v_ashrrev_i32_e32 v115, 31, v114
	v_lshlrev_b64 v[114:115], 7, v[114:115]
	v_lshl_add_u64 v[114:115], s[34:35], 0, v[114:115]
	s_waitcnt lgkmcnt(0)
	global_load_dwordx4 v[74:77], v[114:115], off
	global_load_dwordx4 v[78:81], v[114:115], off offset:16
	global_load_dwordx4 v[82:85], v[114:115], off offset:32
	global_load_dwordx4 v[86:89], v[114:115], off offset:48
	global_load_dwordx4 v[90:93], v[114:115], off offset:64
	global_load_dwordx4 v[94:97], v[114:115], off offset:80
	global_load_dwordx4 v[98:101], v[114:115], off offset:96
	global_load_dwordx4 v[102:105], v[114:115], off offset:112

; #define LAS __attribute__((address_space(3)))
; __device__ __forceinline__ int tidx() { int t = threadIdx.x; asm volatile("" : "+v"(t)); return t; }
; __device__ __forceinline__ int prow0(int pm) { return (pm >> 4) * LP + PADR + (pm & 15) * 256; }
; __device__ __forceinline__ int trow(int i) { return (i >> 4) * LP + 4144 + (i & 15); }
;     __device__ __forceinline__ void prep(int pm, int par, LAS unsigned char* lds) const { if (fold) prep_rowstats(stat, pm, par, lds); }
;     __device__ __forceinline__ void prep(int pm, int par, LAS unsigned char* lds) const { if (!ident) prep_rowstats(stat, pm, par, lds); }
;     __device__ __forceinline__ void prep(int pm, int par, LAS unsigned char* lds) const { prep_rowstats(stat, pm, par, lds); }
; #define G_STAGE(bufoff, gbase) do { _Pragma("unroll") for (int _i = 0; _i < 2; ++_i) \
;         __builtin_amdgcn_global_load_lds((const unsigned*)((const char*)(gbase) + voff[_i]), (LAS unsigned*)(lds + (bufoff) + ldsw + _i * 8192), 16, 0, 0); } while (0)
; __device__ __forceinline__ void prep_rowstats(const float* stat, int pm, int par, LAS unsigned char* lds) {
;     const int t = tidx();
;     if (t < (pm < 64 ? 256 : 64)) {
;         const int row = pm < 64 ? prow0(pm) + t : trow(t); const f32x4* sp = (const f32x4*)(stat + (size_t)row * 32);
;         float s1 = 0.f, s2 = 0.f;
; #pragma unroll
;         for (int q = 0; q < 8; ++q) { const f32x4 v = sp[q]; s1 += v[0] + v[2]; s2 += v[1] + v[3]; }
;         const float mu = s1 * (1.0f / 1024.0f); const float var = fmaxf(s2 * (1.0f / 1024.0f) - mu * mu, 0.f);
;         ((LAS f32x2*)(lds + RS_OFF + par * 2048))[t] = (f32x2){mu, __builtin_amdgcn_rsqf(var + LN_EPS)};
;     }
; }
; template <class Epi>
; __device__ __forceinline__ void gemm_phase(LAS unsigned char* lds, const bf16_t* Ag, const bf16_t* Btg, const int K, const int nM, const int nN, const Epi& E) {
;     ...
;     const char* cA = (const char*)Ag + (size_t)prow0(pm) * rstep; const char* cB = (const char*)Btg + (size_t)pn * tstep;
;     E.prep(pm, par, lds);
;     G_STAGE(G_SB(0, 0), cB); G_STAGE(G_SA(0, 0), cA); G_STAGE(G_SB(0, 1), cB + hstep); G_STAGE(G_SA(0, 1), cA + hstep);
.LBB0_142:
	v_ashrrev_i32_e32 v0, 31, v8
	v_lshrrev_b32_e32 v0, 26, v0
	v_add_u32_e32 v0, v8, v0
	v_ashrrev_i32_e32 v9, 6, v0
	v_bfe_i32 v0, v8, 27, 1
	v_lshlrev_b32_e32 v2, 4, v8
	v_lshrrev_b32_e32 v0, 22, v0
	v_add_u32_e32 v0, v2, v0
	v_and_b32_e32 v0, 0xfffffc00, v0
	v_sub_u32_e32 v0, v2, v0
	v_lshrrev_b32_e32 v3, 4, v0
	v_bitop3_b32 v3, v3, v0, 32 bitop3:0x6c
	v_ashrrev_i32_e32 v0, 31, v0
	v_lshrrev_b32_e32 v0, 26, v0
	s_waitcnt lgkmcnt(0)
	v_lshlrev_b32_e32 v10, 3, v9
	v_add_u32_e32 v0, v3, v0
	v_and_b32_e32 v11, 0x1ffff0, v10
	v_ashrrev_i32_e32 v10, 6, v0
	s_waitcnt vmcnt(15)
	v_mul_i32_i24_e32 v12, 64, v10
	v_sub_u32_e32 v3, v3, v12
	v_ashrrev_i16_sdwa v3, v203, sext(v3) dst_sel:DWORD dst_unused:UNUSED_PAD src0_sel:DWORD src1_sel:BYTE_0
	v_add_u32_e32 v2, 0x2000, v2
	v_bfe_i32 v12, v3, 0, 16
	v_ashrrev_i32_e32 v3, 31, v2
	v_lshrrev_b32_e32 v3, 22, v3
	v_add_u32_e32 v3, v2, v3
	v_ashrrev_i32_e32 v13, 10, v3
	v_mul_i32_i24_e32 v3, 0x400, v13
	v_sub_u32_e32 v2, v2, v3
	v_lshrrev_b32_e32 v3, 4, v2
	v_bitop3_b32 v2, v3, v2, 32 bitop3:0x6c
	v_writelane_b32 v255, s42, 32
	s_ashr_i32 s14, s20, 6
	v_ashrrev_i32_e32 v14, 31, v2
	v_writelane_b32 v255, s43, 33
	s_ashr_i32 s12, s20, 8
	v_lshrrev_b32_e32 v14, 26, v14
	s_lshl_b32 s21, s14, 10
	v_readlane_b32 s42, v253, 28
	v_add_u32_e32 v16, v2, v14
	v_readlane_b32 s43, v253, 29
	s_add_u32 s64, s50, s42
	v_add_u32_e32 v0, v10, v11
	v_lshlrev_b32_e32 v11, 5, v9
	v_lshlrev_b32_e32 v3, 3, v13
	v_ashrrev_i32_e32 v14, 6, v16
	v_and_b32_e32 v16, 0xc0, v16
	s_addc_u32 s65, s51, s43
	v_readlane_b32 s42, v253, 30
	v_and_b32_e32 v11, 32, v11
	v_and_b32_e32 v3, 0x1ffff0, v3
	v_lshlrev_b32_e32 v15, 5, v13
	v_sub_u32_e32 v2, v2, v16
	v_readlane_b32 s43, v253, 31
	s_add_u32 s66, s46, s42
	v_lshl_or_b32 v0, v0, 10, v11
	v_add_u32_e32 v3, v14, v3
	v_and_b32_e32 v15, 32, v15
	v_ashrrev_i16_sdwa v2, v203, sext(v2) dst_sel:DWORD dst_unused:UNUSED_PAD src0_sel:DWORD src1_sel:BYTE_0
	s_addc_u32 s67, s47, s43
	s_add_i32 s72, s21, 0
	v_add_lshl_u32 v0, v0, v12, 1
	v_bfe_i32 v16, v2, 0, 16
	v_lshl_or_b32 v2, v3, 10, v15
	s_add_i32 m0, s72, 0x10000
	v_add_lshl_u32 v2, v2, v16, 1
	global_load_lds_dwordx4 v0, s[66:67]
	s_add_i32 m0, s72, 0x12000
	s_add_i32 s73, s72, 0x2000
	global_load_lds_dwordx4 v2, s[66:67]
	s_mov_b32 m0, s72
	s_add_u32 s42, s66, 0x40000
	global_load_lds_dwordx4 v0, s[64:65]
	s_mov_b32 m0, s73
	s_addc_u32 s43, s67, 0
	global_load_lds_dwordx4 v2, s[64:65]
	s_add_i32 m0, s72, 0x14000
	s_nop 0
	global_load_lds_dwordx4 v0, s[42:43]
	s_add_i32 m0, s72, 0x16000
	s_nop 0
	global_load_lds_dwordx4 v2, s[42:43]
	s_add_u32 s42, s64, 0x40000
	s_addc_u32 s43, s65, 0
	s_add_i32 s74, s72, 0x4000
	s_mov_b32 m0, s74
	s_add_i32 s75, s72, 0x6000
	global_load_lds_dwordx4 v0, s[42:43]
	s_mov_b32 m0, s75
	s_cmp_eq_u32 s69, 0
	s_cbranch_scc1 .Lprol147_b
	v_cmp_gt_i32_e32 vcc, s1, v198
	s_and_saveexec_b64 s[70:71], vcc
	s_cbranch_execz .Lprol147_x
	v_lshl_add_u32 v112, v112, 3, 0
	v_add_u32_e32 v112, 0x20000, v112
	s_waitcnt vmcnt(14)
	v_pk_add_f32 v[114:115], v[74:75], v[76:77]
	s_waitcnt vmcnt(13)
	v_pk_add_f32 v[74:75], v[78:79], v[80:81]
	v_pk_add_f32 v[114:115], v[114:115], 0 op_sel_hi:[1,0]
	s_waitcnt vmcnt(12)
	v_pk_add_f32 v[76:77], v[82:83], v[84:85]
	v_pk_add_f32 v[114:115], v[114:115], v[74:75]
	s_waitcnt vmcnt(11)
	v_pk_add_f32 v[78:79], v[86:87], v[88:89]
	v_pk_add_f32 v[114:115], v[114:115], v[76:77]
	s_waitcnt vmcnt(10)
	v_pk_add_f32 v[80:81], v[90:91], v[92:93]
	v_pk_add_f32 v[114:115], v[114:115], v[78:79]
	s_waitcnt vmcnt(9)
	v_pk_add_f32 v[82:83], v[94:95], v[96:97]
	v_pk_add_f32 v[114:115], v[114:115], v[80:81]
	s_waitcnt vmcnt(8)
	v_pk_add_f32 v[84:85], v[98:99], v[100:101]
	v_pk_add_f32 v[114:115], v[114:115], v[82:83]
	s_waitcnt vmcnt(7)
	v_pk_add_f32 v[74:75], v[102:103], v[104:105]
	v_pk_add_f32 v[114:115], v[114:115], v[84:85]
	s_nop 0
	v_pk_add_f32 v[114:115], v[114:115], v[74:75]
	s_nop 0
	v_pk_mul_f32 v[114:115], v[114:115], s[0:1] op_sel_hi:[1,0]
	s_nop 0
	v_fma_f32 v115, -v114, v114, v115
	v_max_f32_e32 v115, 0, v115
	v_add_f32_e32 v115, 0x3727c5ac, v115
	v_rsq_f32_e32 v115, v115
	ds_write_b64 v112, v[114:115]

; #define G_STAGE(bufoff, gbase) do { _Pragma("unroll") for (int _i = 0; _i < 2; ++_i) \
;         __builtin_amdgcn_global_load_lds((const unsigned*)((const char*)(gbase) + voff[_i]), (LAS unsigned*)(lds + (bufoff) + ldsw + _i * 8192), 16, 0, 0); } while (0)
; #define G_WAIT_V(n) asm volatile("s_waitcnt vmcnt(" #n ")" ::: "memory")
; #define G_BAR __builtin_amdgcn_s_barrier()
; template <class Epi>
; __device__ __forceinline__ void gemm_phase(LAS unsigned char* lds, const bf16_t* Ag, const bf16_t* Btg, const int K, const int nM, const int nN, const Epi& E) {
;     ...
;     G_STAGE(G_SB(0, 0), cB); G_STAGE(G_SA(0, 0), cA); G_STAGE(G_SB(0, 1), cB + hstep); G_STAGE(G_SA(0, 1), cA + hstep);
;     if (wr == 1) G_BAR;
;     G_WAIT_V(4); G_BAR;
.Lprol147_b:
	s_cmp_lg_u32 s12, 1
	global_load_lds_dwordx4 v2, s[42:43]
	s_cbranch_scc1 .LBB0_144
	s_barrier

; #define LAS __attribute__((address_space(3)))
; __device__ __forceinline__ int tidx() { int t = threadIdx.x; asm volatile("" : "+v"(t)); return t; }
; __device__ __forceinline__ int prow0(int pm) { return (pm >> 4) * LP + PADR + (pm & 15) * 256; }
; __device__ __forceinline__ int trow(int i) { return (i >> 4) * LP + 4144 + (i & 15); }
;     __device__ __forceinline__ void prep(int pm, int par, LAS unsigned char* lds) const { if (fold) prep_rowstats(stat, pm, par, lds); }
;     __device__ __forceinline__ void prep(int pm, int par, LAS unsigned char* lds) const { if (!ident) prep_rowstats(stat, pm, par, lds); }
;     __device__ __forceinline__ void prep(int pm, int par, LAS unsigned char* lds) const { prep_rowstats(stat, pm, par, lds); }
; #define G_STAGE(bufoff, gbase) do { _Pragma("unroll") for (int _i = 0; _i < 2; ++_i) \
;         __builtin_amdgcn_global_load_lds((const unsigned*)((const char*)(gbase) + voff[_i]), (LAS unsigned*)(lds + (bufoff) + ldsw + _i * 8192), 16, 0, 0); } while (0)
; __device__ __forceinline__ void prep_rowstats(const float* stat, int pm, int par, LAS unsigned char* lds) {
;     const int t = tidx();
;     if (t < (pm < 64 ? 256 : 64)) {
;         const int row = pm < 64 ? prow0(pm) + t : trow(t); const f32x4* sp = (const f32x4*)(stat + (size_t)row * 32);
;         float s1 = 0.f, s2 = 0.f;
; #pragma unroll
;         for (int q = 0; q < 8; ++q) { const f32x4 v = sp[q]; s1 += v[0] + v[2]; s2 += v[1] + v[3]; }
;         const float mu = s1 * (1.0f / 1024.0f); const float var = fmaxf(s2 * (1.0f / 1024.0f) - mu * mu, 0.f);
;         ((LAS f32x2*)(lds + RS_OFF + par * 2048))[t] = (f32x2){mu, __builtin_amdgcn_rsqf(var + LN_EPS)};
;     }
; }
; template <class Epi>
; __device__ __forceinline__ void gemm_phase(LAS unsigned char* lds, const bf16_t* Ag, const bf16_t* Btg, const int K, const int nM, const int nN, const Epi& E) {
;     ...
;     const char* cA = (const char*)Ag + (size_t)prow0(pm) * rstep; const char* cB = (const char*)Btg + (size_t)pn * tstep;
;     E.prep(pm, par, lds);
;     G_STAGE(G_SB(0, 0), cB); G_STAGE(G_SA(0, 0), cA); G_STAGE(G_SB(0, 1), cB + hstep); G_STAGE(G_SA(0, 1), cA + hstep);
.LBB0_731:
	v_readlane_b32 s6, v253, 7
	s_waitcnt vmcnt(17)
	v_mov_b32_e32 v9, v198
	v_readlane_b32 s7, v253, 8
	s_load_dword s13, s[6:7], 0x0
	s_add_u32 s6, s84, 0x3100000
	s_addc_u32 s7, s85, 0
	s_and_b64 vcc, exec, s[42:43]
	v_readfirstlane_b32 s64, v9
	s_mov_b32 s77, 0
	s_cbranch_vccnz .LBB0_769
	v_mov_b32_e32 v112, v198
	s_nop 0
	v_cmp_gt_i32_e32 vcc, s1, v112
	s_and_saveexec_b64 s[24:25], vcc
	s_cbranch_execz .LBB0_734
	s_mov_b32 s77, 1
	v_readlane_b32 s14, v253, 47
	v_readlane_b32 s15, v253, 48
	s_nop 0
	v_add_u32_e32 v114, s14, v112
	v_ashrrev_i32_e32 v115, 31, v114
	v_lshlrev_b64 v[114:115], 7, v[114:115]
	v_lshl_add_u64 v[114:115], s[18:19], 0, v[114:115]
	s_waitcnt lgkmcnt(0)
	global_load_dwordx4 v[74:77], v[114:115], off
	global_load_dwordx4 v[78:81], v[114:115], off offset:16
	global_load_dwordx4 v[82:85], v[114:115], off offset:32
	global_load_dwordx4 v[86:89], v[114:115], off offset:48
	global_load_dwordx4 v[90:93], v[114:115], off offset:64
	global_load_dwordx4 v[94:97], v[114:115], off offset:80
	global_load_dwordx4 v[98:101], v[114:115], off offset:96
	global_load_dwordx4 v[102:105], v[114:115], off offset:112
.LBB0_734:
	s_or_b64 exec, exec, s[24:25]
	v_ashrrev_i32_e32 v0, 31, v9
	v_lshrrev_b32_e32 v0, 26, v0
	v_add_u32_e32 v0, v9, v0
	v_ashrrev_i32_e32 v8, 6, v0
	v_bfe_i32 v0, v9, 27, 1
	v_lshlrev_b32_e32 v2, 4, v9
	v_lshrrev_b32_e32 v0, 22, v0
	v_add_u32_e32 v0, v2, v0
	v_and_b32_e32 v0, 0xfffffc00, v0
	v_sub_u32_e32 v0, v2, v0
	v_lshrrev_b32_e32 v3, 4, v0
	v_bitop3_b32 v3, v3, v0, 32 bitop3:0x6c
	v_ashrrev_i32_e32 v0, 31, v0
	v_lshrrev_b32_e32 v0, 26, v0
	v_lshlrev_b32_e32 v10, 3, v8
	v_add_u32_e32 v0, v3, v0
	v_and_b32_e32 v11, 0x7fff0, v10
	v_ashrrev_i32_e32 v10, 6, v0
	s_waitcnt vmcnt(15)
	v_mul_i32_i24_e32 v12, 64, v10
	v_sub_u32_e32 v3, v3, v12
	v_ashrrev_i16_sdwa v3, v203, sext(v3) dst_sel:DWORD dst_unused:UNUSED_PAD src0_sel:DWORD src1_sel:BYTE_0
	v_add_u32_e32 v2, 0x2000, v2
	v_bfe_i32 v12, v3, 0, 16
	v_ashrrev_i32_e32 v3, 31, v2
	v_lshrrev_b32_e32 v3, 22, v3
	v_add_u32_e32 v3, v2, v3
	s_waitcnt lgkmcnt(0)
	v_ashrrev_i32_e32 v13, 10, v3
	v_mul_i32_i24_e32 v3, 0x400, v13
	v_sub_u32_e32 v2, v2, v3
	v_lshrrev_b32_e32 v3, 4, v2
	v_bitop3_b32 v2, v3, v2, 32 bitop3:0x6c
	s_ashr_i32 s14, s64, 6
	v_ashrrev_i32_e32 v14, 31, v2
	s_ashr_i32 s12, s64, 8
	v_lshrrev_b32_e32 v14, 26, v14
	s_lshl_b32 s65, s14, 10
	v_readlane_b32 s24, v253, 49
	v_add_u32_e32 v16, v2, v14
	v_readlane_b32 s25, v253, 50
	s_add_u32 s56, s86, s24
	v_add_u32_e32 v0, v10, v11
	v_lshlrev_b32_e32 v11, 5, v8
	v_lshlrev_b32_e32 v3, 3, v13
	v_ashrrev_i32_e32 v14, 6, v16
	v_and_b32_e32 v16, 0xc0, v16
	s_addc_u32 s57, s87, s25
	v_readlane_b32 s24, v253, 53
	v_and_b32_e32 v11, 32, v11
	v_and_b32_e32 v3, 0x7fff0, v3
	v_lshlrev_b32_e32 v15, 5, v13
	v_sub_u32_e32 v2, v2, v16
	v_readlane_b32 s25, v253, 54
	s_add_u32 s58, s6, s24
	v_lshl_or_b32 v0, v0, 12, v11
	v_add_u32_e32 v3, v14, v3
	v_and_b32_e32 v15, 32, v15
	v_ashrrev_i16_sdwa v2, v203, sext(v2) dst_sel:DWORD dst_unused:UNUSED_PAD src0_sel:DWORD src1_sel:BYTE_0
	s_addc_u32 s59, s7, s25
	s_add_i32 s66, s65, 0
	v_add_lshl_u32 v0, v0, v12, 1
	v_bfe_i32 v16, v2, 0, 16
	v_lshl_or_b32 v2, v3, 12, v15
	s_add_i32 m0, s66, 0x10000
	v_add_lshl_u32 v2, v2, v16, 1
	global_load_lds_dwordx4 v0, s[58:59]
	s_add_i32 m0, s66, 0x12000
	s_add_i32 s67, s66, 0x2000
	global_load_lds_dwordx4 v2, s[58:59]
	s_mov_b32 m0, s66
	s_add_u32 s24, s58, 0x100000
	global_load_lds_dwordx4 v0, s[56:57]
	s_mov_b32 m0, s67
	s_addc_u32 s25, s59, 0
	global_load_lds_dwordx4 v2, s[56:57]
	s_add_i32 m0, s66, 0x14000
	s_nop 0
	global_load_lds_dwordx4 v0, s[24:25]
	s_add_i32 m0, s66, 0x16000
	s_nop 0
	global_load_lds_dwordx4 v2, s[24:25]
	s_add_u32 s24, s56, 0x100000
	s_addc_u32 s25, s57, 0
	s_add_i32 s68, s66, 0x4000
	s_mov_b32 m0, s68
	s_add_i32 s69, s66, 0x6000
	global_load_lds_dwordx4 v0, s[24:25]
	s_mov_b32 m0, s69
	s_cmp_eq_u32 s77, 0
	s_cbranch_scc1 .Lprol738_b
	v_cmp_gt_i32_e32 vcc, s1, v198
	s_and_saveexec_b64 s[78:79], vcc
	s_cbranch_execz .Lprol738_x
	v_lshl_add_u32 v112, v112, 3, 0
	v_add_u32_e32 v112, 0x20000, v112
	s_waitcnt vmcnt(14)
	v_pk_add_f32 v[114:115], v[74:75], v[76:77]
	s_waitcnt vmcnt(13)
	v_pk_add_f32 v[74:75], v[78:79], v[80:81]
	v_pk_add_f32 v[114:115], v[114:115], 0 op_sel_hi:[1,0]
	s_waitcnt vmcnt(12)
	v_pk_add_f32 v[76:77], v[82:83], v[84:85]
	v_pk_add_f32 v[114:115], v[114:115], v[74:75]
	s_waitcnt vmcnt(11)
	v_pk_add_f32 v[78:79], v[86:87], v[88:89]
	v_pk_add_f32 v[114:115], v[114:115], v[76:77]
	s_waitcnt vmcnt(10)
	v_pk_add_f32 v[80:81], v[90:91], v[92:93]
	v_pk_add_f32 v[114:115], v[114:115], v[78:79]
	s_waitcnt vmcnt(9)
	v_pk_add_f32 v[82:83], v[94:95], v[96:97]
	v_pk_add_f32 v[114:115], v[114:115], v[80:81]
	s_waitcnt vmcnt(8)
	v_pk_add_f32 v[84:85], v[98:99], v[100:101]
	v_pk_add_f32 v[114:115], v[114:115], v[82:83]
	s_waitcnt vmcnt(7)
	v_pk_add_f32 v[74:75], v[102:103], v[104:105]
	v_pk_add_f32 v[114:115], v[114:115], v[84:85]
	s_nop 0
	v_pk_add_f32 v[114:115], v[114:115], v[74:75]
	s_nop 0
	v_pk_mul_f32 v[114:115], v[114:115], s[0:1] op_sel_hi:[1,0]
	s_nop 0
	v_fma_f32 v115, -v114, v114, v115
	v_max_f32_e32 v115, 0, v115
	v_add_f32_e32 v115, 0x3727c5ac, v115
	v_rsq_f32_e32 v115, v115
	ds_write_b64 v112, v[114:115]

; #define G_STAGE(bufoff, gbase) do { _Pragma("unroll") for (int _i = 0; _i < 2; ++_i) \
;         __builtin_amdgcn_global_load_lds((const unsigned*)((const char*)(gbase) + voff[_i]), (LAS unsigned*)(lds + (bufoff) + ldsw + _i * 8192), 16, 0, 0); } while (0)
; #define G_WAIT_V(n) asm volatile("s_waitcnt vmcnt(" #n ")" ::: "memory")
; #define G_BAR __builtin_amdgcn_s_barrier()
; template <class Epi>
; __device__ __forceinline__ void gemm_phase(LAS unsigned char* lds, const bf16_t* Ag, const bf16_t* Btg, const int K, const int nM, const int nN, const Epi& E) {
;     ...
;     G_STAGE(G_SB(0, 0), cB); G_STAGE(G_SA(0, 0), cA); G_STAGE(G_SB(0, 1), cB + hstep); G_STAGE(G_SA(0, 1), cA + hstep);
;     if (wr == 1) G_BAR;
;     G_WAIT_V(4); G_BAR;
.Lprol738_b:
	s_cmp_lg_u32 s12, 1
	global_load_lds_dwordx4 v2, s[24:25]
	s_cbranch_scc1 .LBB0_736
	s_barrier

; #define LAS __attribute__((address_space(3)))
; __device__ __forceinline__ int tidx() { int t = threadIdx.x; asm volatile("" : "+v"(t)); return t; }
; __device__ __forceinline__ int prow0(int pm) { return (pm >> 4) * LP + PADR + (pm & 15) * 256; }
; __device__ __forceinline__ int trow(int i) { return (i >> 4) * LP + 4144 + (i & 15); }
; __device__ __forceinline__ void prep_rowstats(const float* stat, int pm, int par, LAS unsigned char* lds) {
;     const int t = tidx();
;     if (t < (pm < 64 ? 256 : 64)) {
;         const int row = pm < 64 ? prow0(pm) + t : trow(t); const f32x4* sp = (const f32x4*)(stat + (size_t)row * 32);
;         float s1 = 0.f, s2 = 0.f;
; #pragma unroll
;         for (int q = 0; q < 8; ++q) { const f32x4 v = sp[q]; s1 += v[0] + v[2]; s2 += v[1] + v[3]; }
.LBB0_832:
	v_readlane_b32 s6, v255, 27
	s_nop 1
	s_cmp_eq_u32 s6, 2
	s_cbranch_scc1 .Lk2_conv_done
	s_add_u32 s18, s86, 0xee8d800
	s_addc_u32 s19, s87, 0
	s_add_u32 s20, s86, 0xee90c00
	s_addc_u32 s21, s87, 0
	v_readlane_b32 s6, v255, 25
	s_cmp_lt_i32 s6, 1
	s_cselect_b64 s[42:43], -1, 0
	s_cmp_gt_i32 s6, 0
	s_cselect_b64 s[12:13], -1, 0
	v_readlane_b32 s14, v253, 41
	v_readlane_b32 s7, v255, 26
	s_add_u32 s6, s84, 0x2080000
	s_waitcnt vmcnt(16)
	v_mov_b32_e32 v16, v198
	v_readlane_b32 s15, v253, 42
	v_cndmask_b32_e64 v0, 0, 1, s[12:13]
	s_addc_u32 s7, s85, 0
	s_andn2_b64 vcc, exec, s[14:15]
	v_readfirstlane_b32 s58, v16
	v_cmp_ne_u32_e64 s[40:41], 1, v0
	s_cbranch_vccnz .LBB0_881
	s_and_b64 vcc, exec, s[40:41]
	s_mov_b32 s79, 0
	s_cbranch_vccnz .LBB0_837
	v_mov_b32_e32 v112, v198
	s_nop 0
	v_cmp_gt_i32_e32 vcc, s1, v112
	s_and_saveexec_b64 s[22:23], vcc
	s_cbranch_execz .LBB0_836
	s_mov_b32 s79, 1
	v_readlane_b32 s14, v253, 47
	v_readlane_b32 s15, v253, 48
	s_nop 0
	v_add_u32_e32 v114, s14, v112
	v_ashrrev_i32_e32 v115, 31, v114
	v_lshlrev_b64 v[114:115], 7, v[114:115]
	v_lshl_add_u64 v[114:115], s[34:35], 0, v[114:115]
	global_load_dwordx4 v[72:75], v[114:115], off
	global_load_dwordx4 v[76:79], v[114:115], off offset:16
	global_load_dwordx4 v[82:85], v[114:115], off offset:32
	global_load_dwordx4 v[86:89], v[114:115], off offset:48
	global_load_dwordx4 v[90:93], v[114:115], off offset:64
	global_load_dwordx4 v[94:97], v[114:115], off offset:80
	global_load_dwordx4 v[98:101], v[114:115], off offset:96
	global_load_dwordx4 v[102:105], v[114:115], off offset:112

; #define LAS __attribute__((address_space(3)))
; __device__ __forceinline__ int tidx() { int t = threadIdx.x; asm volatile("" : "+v"(t)); return t; }
; __device__ __forceinline__ int prow0(int pm) { return (pm >> 4) * LP + PADR + (pm & 15) * 256; }
; __device__ __forceinline__ int trow(int i) { return (i >> 4) * LP + 4144 + (i & 15); }
;     __device__ __forceinline__ void prep(int pm, int par, LAS unsigned char* lds) const { if (fold) prep_rowstats(stat, pm, par, lds); }
;     __device__ __forceinline__ void prep(int pm, int par, LAS unsigned char* lds) const { if (!ident) prep_rowstats(stat, pm, par, lds); }
;     __device__ __forceinline__ void prep(int pm, int par, LAS unsigned char* lds) const { prep_rowstats(stat, pm, par, lds); }
; #define G_STAGE(bufoff, gbase) do { _Pragma("unroll") for (int _i = 0; _i < 2; ++_i) \
;         __builtin_amdgcn_global_load_lds((const unsigned*)((const char*)(gbase) + voff[_i]), (LAS unsigned*)(lds + (bufoff) + ldsw + _i * 8192), 16, 0, 0); } while (0)
; __device__ __forceinline__ void prep_rowstats(const float* stat, int pm, int par, LAS unsigned char* lds) {
;     const int t = tidx();
;     if (t < (pm < 64 ? 256 : 64)) {
;         const int row = pm < 64 ? prow0(pm) + t : trow(t); const f32x4* sp = (const f32x4*)(stat + (size_t)row * 32);
;         float s1 = 0.f, s2 = 0.f;
; #pragma unroll
;         for (int q = 0; q < 8; ++q) { const f32x4 v = sp[q]; s1 += v[0] + v[2]; s2 += v[1] + v[3]; }
;         const float mu = s1 * (1.0f / 1024.0f); const float var = fmaxf(s2 * (1.0f / 1024.0f) - mu * mu, 0.f);
;         ((LAS f32x2*)(lds + RS_OFF + par * 2048))[t] = (f32x2){mu, __builtin_amdgcn_rsqf(var + LN_EPS)};
;     }
; }
; template <class Epi>
; __device__ __forceinline__ void gemm_phase(LAS unsigned char* lds, const bf16_t* Ag, const bf16_t* Btg, const int K, const int nM, const int nN, const Epi& E) {
;     ...
;     const char* cA = (const char*)Ag + (size_t)prow0(pm) * rstep; const char* cB = (const char*)Btg + (size_t)pn * tstep;
;     E.prep(pm, par, lds);
;     G_STAGE(G_SB(0, 0), cB); G_STAGE(G_SA(0, 0), cA); G_STAGE(G_SB(0, 1), cB + hstep); G_STAGE(G_SA(0, 1), cA + hstep);
.LBB0_837:
	v_ashrrev_i32_e32 v0, 31, v16
	v_lshrrev_b32_e32 v0, 26, v0
	v_add_u32_e32 v0, v16, v0
	v_ashrrev_i32_e32 v17, 6, v0
	v_bfe_i32 v0, v16, 27, 1
	v_lshlrev_b32_e32 v2, 4, v16
	v_lshrrev_b32_e32 v0, 22, v0
	v_add_u32_e32 v0, v2, v0
	v_and_b32_e32 v0, 0xfffffc00, v0
	v_sub_u32_e32 v0, v2, v0
	v_lshrrev_b32_e32 v3, 4, v0
	v_bitop3_b32 v3, v3, v0, 32 bitop3:0x6c
	v_ashrrev_i32_e32 v0, 31, v0
	v_lshrrev_b32_e32 v0, 26, v0
	v_add_u32_e32 v0, v3, v0
	v_ashrrev_i32_e32 v18, 6, v0
	v_mul_i32_i24_e32 v9, 64, v18
	v_sub_u32_e32 v3, v3, v9
	v_lshlrev_b32_e32 v8, 3, v17
	v_lshlrev_b32_e32 v0, 5, v17
	v_ashrrev_i16_sdwa v3, v203, sext(v3) dst_sel:DWORD dst_unused:UNUSED_PAD src0_sel:DWORD src1_sel:BYTE_0
	v_and_b32_e32 v8, 0x1ffff0, v8
	v_and_b32_e32 v0, 32, v0
	v_bfe_i32 v19, v3, 0, 16
	v_add_u32_e32 v0, v0, v19
	v_add_lshl_u32 v3, v18, v8, 11
	v_add_u32_e32 v2, 0x2000, v2
	v_lshl_add_u32 v0, v0, 1, v3
	v_ashrrev_i32_e32 v3, 31, v2
	v_lshrrev_b32_e32 v3, 22, v3
	v_add_u32_e32 v3, v2, v3
	s_waitcnt vmcnt(13)
	v_ashrrev_i32_e32 v20, 10, v3
	v_mul_i32_i24_e32 v3, 0x400, v20
	v_sub_u32_e32 v2, v2, v3
	v_lshrrev_b32_e32 v3, 4, v2
	v_bitop3_b32 v2, v3, v2, 32 bitop3:0x6c
	v_ashrrev_i32_e32 v8, 31, v2
	s_ashr_i32 s15, s58, 6
	v_lshrrev_b32_e32 v8, 26, v8
	s_ashr_i32 s14, s58, 8
	v_add_u32_e32 v8, v2, v8
	s_lshl_b32 s59, s15, 10
	v_readlane_b32 s22, v253, 28
	v_ashrrev_i32_e32 v21, 6, v8
	v_and_b32_e32 v8, 0xc0, v8
	v_readlane_b32 s23, v253, 29
	s_add_u32 s50, s36, s22
	v_sub_u32_e32 v2, v2, v8
	s_addc_u32 s51, s37, s23
	v_readlane_b32 s22, v253, 30
	v_lshlrev_b32_e32 v3, 3, v20
	v_lshlrev_b32_e32 v9, 5, v20
	v_ashrrev_i16_sdwa v2, v203, sext(v2) dst_sel:DWORD dst_unused:UNUSED_PAD src0_sel:DWORD src1_sel:BYTE_0
	v_readlane_b32 s23, v253, 31
	s_add_u32 s52, s6, s22
	v_and_b32_e32 v3, 0x1ffff0, v3
	v_and_b32_e32 v9, 32, v9
	v_bfe_i32 v22, v2, 0, 16
	s_addc_u32 s53, s7, s23
	s_add_i32 s60, s59, 0
	v_add_u32_e32 v2, v9, v22
	v_add_lshl_u32 v3, v21, v3, 11
	s_add_i32 m0, s60, 0x10000
	v_lshl_add_u32 v2, v2, 1, v3
	global_load_lds_dwordx4 v0, s[52:53]
	s_add_i32 m0, s60, 0x12000
	s_add_i32 s61, s60, 0x2000
	global_load_lds_dwordx4 v2, s[52:53]
	s_mov_b32 m0, s60
	s_add_u32 s22, s52, 0x40000
	global_load_lds_dwordx4 v0, s[50:51]
	s_mov_b32 m0, s61
	s_addc_u32 s23, s53, 0
	global_load_lds_dwordx4 v2, s[50:51]
	s_add_i32 m0, s60, 0x14000
	v_mov_b32_e32 v3, v1
	global_load_lds_dwordx4 v0, s[22:23]
	s_add_i32 m0, s60, 0x16000
	v_lshl_add_u64 v[14:15], s[52:53], 0, v[0:1]
	global_load_lds_dwordx4 v2, s[22:23]
	s_add_u32 s22, s50, 0x40000
	s_addc_u32 s23, s51, 0
	s_add_i32 s62, s60, 0x4000
	s_mov_b32 m0, s62
	s_add_i32 s63, s60, 0x6000
	global_load_lds_dwordx4 v0, s[22:23]
	s_mov_b32 m0, s63
	v_lshl_add_u64 v[12:13], s[52:53], 0, v[2:3]
	global_load_lds_dwordx4 v2, s[22:23]
	v_lshl_add_u64 v[10:11], s[50:51], 0, v[0:1]
	s_cmp_eq_u32 s79, 0
	s_cbranch_scc1 .Lprol842_b
	v_cmp_gt_i32_e32 vcc, s1, v198
	s_and_saveexec_b64 s[70:71], vcc
	s_cbranch_execz .Lprol842_x
	v_lshl_add_u32 v112, v112, 3, 0
	v_add_u32_e32 v112, 0x20000, v112
	s_waitcnt vmcnt(15)
	v_pk_add_f32 v[114:115], v[72:73], v[74:75]
	s_waitcnt vmcnt(14)
	v_pk_add_f32 v[72:73], v[76:77], v[78:79]
	v_pk_add_f32 v[114:115], v[114:115], 0 op_sel_hi:[1,0]
	s_waitcnt vmcnt(13)
	v_pk_add_f32 v[74:75], v[82:83], v[84:85]
	v_pk_add_f32 v[114:115], v[114:115], v[72:73]
	s_waitcnt vmcnt(12)
	v_pk_add_f32 v[76:77], v[86:87], v[88:89]
	v_pk_add_f32 v[114:115], v[114:115], v[74:75]
	s_waitcnt vmcnt(11)
	v_pk_add_f32 v[78:79], v[90:91], v[92:93]
	v_pk_add_f32 v[114:115], v[114:115], v[76:77]
	s_waitcnt vmcnt(10)
	v_pk_add_f32 v[82:83], v[94:95], v[96:97]
	v_pk_add_f32 v[114:115], v[114:115], v[78:79]
	s_waitcnt vmcnt(9)
	v_pk_add_f32 v[84:85], v[98:99], v[100:101]
	v_pk_add_f32 v[114:115], v[114:115], v[82:83]
	s_waitcnt vmcnt(8)
	v_pk_add_f32 v[72:73], v[102:103], v[104:105]
	v_pk_add_f32 v[114:115], v[114:115], v[84:85]
	s_nop 0
	v_pk_add_f32 v[114:115], v[114:115], v[72:73]
	s_nop 0
	v_pk_mul_f32 v[114:115], v[114:115], s[0:1] op_sel_hi:[1,0]
	s_nop 0
	v_fma_f32 v115, -v114, v114, v115
	v_max_f32_e32 v115, 0, v115
	v_add_f32_e32 v115, 0x3727c5ac, v115
	v_rsq_f32_e32 v115, v115
	ds_write_b64 v112, v[114:115]

; #define G_STAGE(bufoff, gbase) do { _Pragma("unroll") for (int _i = 0; _i < 2; ++_i) \
;         __builtin_amdgcn_global_load_lds((const unsigned*)((const char*)(gbase) + voff[_i]), (LAS unsigned*)(lds + (bufoff) + ldsw + _i * 8192), 16, 0, 0); } while (0)
; #define G_WAIT_V(n) asm volatile("s_waitcnt vmcnt(" #n ")" ::: "memory")
; #define G_BAR __builtin_amdgcn_s_barrier()
; template <class Epi>
; __device__ __forceinline__ void gemm_phase(LAS unsigned char* lds, const bf16_t* Ag, const bf16_t* Btg, const int K, const int nM, const int nN, const Epi& E) {
;     ...
;     G_STAGE(G_SB(0, 0), cB); G_STAGE(G_SA(0, 0), cA); G_STAGE(G_SB(0, 1), cB + hstep); G_STAGE(G_SA(0, 1), cA + hstep);
;     if (wr == 1) G_BAR;
;     G_WAIT_V(4); G_BAR;
.Lprol842_b:
	s_cmp_lg_u32 s14, 1
	v_lshl_add_u64 v[8:9], s[50:51], 0, v[2:3]
	s_cbranch_scc1 .LBB0_839
	s_barrier
